# latent attention kv loop: K/V LDS fragment reads hoisted to tile start, tile-consumed barrier and next-tile LDS writes moved into PV MFMAs
# speedup vs baseline: 1.0000x; 1.0000x over previous
.Lattn_d_top:
	s_cbranch_vccnz .LBB0_347
	s_cmp_gt_u32 s12, 5
	s_mov_b64 s[8:9], -1
	s_cbranch_scc0 .LBB0_344
	v_add_u32_e32 v0, s10, v136
	v_add_u32_e32 v0, 0x2000, v0
	v_mad_i64_i32 v[2:3], s[8:9], v0, s33, v[124:125]
	s_mov_b64 s[8:9], 0

.LBB0_347:
	ds_read_b128 v[166:169], v134
	ds_read_b128 v[170:173], v134 offset:64
	ds_read_b128 v[174:177], v134 offset:2304
	ds_read_b128 v[178:181], v134 offset:2368
	ds_read_b128 v[196:199], v134 offset:4608
	ds_read_b128 v[200:203], v134 offset:4672
	ds_read_b128 v[204:207], v134 offset:6912
	ds_read_b128 v[212:215], v134 offset:6976
	ds_read_b128 v[216:219], v135 offset:9216
	ds_read_b128 v[220:223], v135 offset:9280
	ds_read_b128 v[224:227], v135 offset:11520
	ds_read_b128 v[228:231], v135 offset:11584
	ds_read_b128 v[232:235], v135 offset:13824
	ds_read_b128 v[240:243], v135 offset:13888
	s_waitcnt lgkmcnt(13)
	v_mfma_f32_16x16x32_bf16 v[100:103], v[166:169], v[4:7], 0
	v_mfma_f32_16x16x32_bf16 v[84:87], v[166:169], v[12:15], 0
	ds_read_b128 v[244:247], v135 offset:16128
	ds_read_b128 v[248:251], v135 offset:16192
	s_waitcnt lgkmcnt(14)
	v_mfma_f32_16x16x32_bf16 v[100:103], v[170:173], v[8:11], v[100:103]
	v_mfma_f32_16x16x32_bf16 v[84:87], v[170:173], v[16:19], v[84:87]
	s_waitcnt lgkmcnt(13)
	v_mfma_f32_16x16x32_bf16 v[104:107], v[174:177], v[4:7], 0
	v_mfma_f32_16x16x32_bf16 v[88:91], v[174:177], v[12:15], 0
	s_waitcnt lgkmcnt(12)
	v_mfma_f32_16x16x32_bf16 v[104:107], v[178:181], v[8:11], v[104:107]
	v_mfma_f32_16x16x32_bf16 v[88:91], v[178:181], v[16:19], v[88:91]
	s_waitcnt lgkmcnt(11)
	v_mfma_f32_16x16x32_bf16 v[108:111], v[196:199], v[4:7], 0
	v_mfma_f32_16x16x32_bf16 v[92:95], v[196:199], v[12:15], 0
	v_max3_f32 v0, v100, s54, v101
	v_max3_f32 v0, v0, v102, v103
	s_waitcnt lgkmcnt(10)
	v_mfma_f32_16x16x32_bf16 v[108:111], v[200:203], v[8:11], v[108:111]
	v_mfma_f32_16x16x32_bf16 v[92:95], v[200:203], v[16:19], v[92:95]
	s_waitcnt lgkmcnt(9)
	v_mfma_f32_16x16x32_bf16 v[112:115], v[204:207], v[4:7], 0
	v_mfma_f32_16x16x32_bf16 v[96:99], v[204:207], v[12:15], 0
	v_max3_f32 v0, v0, v104, v105
	v_max3_f32 v0, v0, v106, v107
	s_waitcnt lgkmcnt(8)
	v_mfma_f32_16x16x32_bf16 v[112:115], v[212:215], v[8:11], v[112:115]
	v_mfma_f32_16x16x32_bf16 v[96:99], v[212:215], v[16:19], v[96:99]
	v_max3_f32 v0, v0, v108, v109
	v_max3_f32 v0, v0, v110, v111
	s_nop 5
	v_max3_f32 v0, v0, v112, v113
	v_max3_f32 v0, v0, v114, v115
	v_mov_b32_e32 v2, v0
	s_nop 1
	v_permlane16_swap_b32_e32 v0, v2
	v_max_f32_e32 v2, v2, v2
	v_max_f32_e32 v0, v0, v0
	v_max_f32_e32 v0, v0, v2
	v_mov_b32_e32 v2, v0
	s_nop 1
	v_permlane32_swap_b32_e32 v0, v2
	v_max_f32_e32 v2, v2, v2
	v_max_f32_e32 v0, v0, v0
	v_max_f32_e32 v0, v0, v2
	v_add_f32_e32 v2, 0x41000000, v138
	v_cmp_gt_f32_e32 vcc, v0, v2
	s_cbranch_vccz .LBB0_349
	v_max_f32_e32 v0, v0, v0
	v_max_f32_e32 v2, v138, v138
	v_max_f32_e32 v2, v2, v0
	v_sub_f32_e32 v0, v138, v2
	v_exp_f32_e32 v0, v0
	v_mov_b32_e32 v138, v2
	v_mul_f32_e32 v140, v140, v0
	v_pk_mul_f32 v[82:83], v[82:83], v[0:1] op_sel_hi:[1,0]
	v_pk_mul_f32 v[80:81], v[80:81], v[0:1] op_sel_hi:[1,0]
	v_pk_mul_f32 v[74:75], v[74:75], v[0:1] op_sel_hi:[1,0]
	v_pk_mul_f32 v[72:73], v[72:73], v[0:1] op_sel_hi:[1,0]
	v_pk_mul_f32 v[66:67], v[66:67], v[0:1] op_sel_hi:[1,0]
	v_pk_mul_f32 v[64:65], v[64:65], v[0:1] op_sel_hi:[1,0]
	v_pk_mul_f32 v[58:59], v[58:59], v[0:1] op_sel_hi:[1,0]
	v_pk_mul_f32 v[56:57], v[56:57], v[0:1] op_sel_hi:[1,0]

.LBB0_351:
	v_sub_f32_e32 v0, v100, v138
	v_exp_f32_e32 v157, v0
	v_sub_f32_e32 v0, v101, v138
	v_exp_f32_e32 v158, v0
	v_sub_f32_e32 v0, v102, v138
	v_exp_f32_e32 v159, v0
	v_sub_f32_e32 v0, v103, v138
	v_sub_f32_e32 v2, v85, v137
	v_exp_f32_e32 v160, v0
	v_sub_f32_e32 v0, v104, v138
	v_exp_f32_e32 v141, v2
	v_sub_f32_e32 v2, v86, v137
	v_exp_f32_e32 v104, v0
	v_sub_f32_e32 v0, v105, v138
	v_exp_f32_e32 v142, v2
	v_sub_f32_e32 v2, v87, v137
	v_exp_f32_e32 v105, v0
	v_sub_f32_e32 v0, v106, v138
	v_exp_f32_e32 v143, v2
	v_sub_f32_e32 v2, v88, v137
	v_exp_f32_e32 v106, v0
	v_sub_f32_e32 v0, v107, v138
	v_exp_f32_e32 v144, v2
	v_sub_f32_e32 v2, v89, v137
	v_exp_f32_e32 v107, v0
	v_sub_f32_e32 v0, v108, v138
	v_exp_f32_e32 v145, v2
	v_sub_f32_e32 v2, v90, v137
	v_exp_f32_e32 v108, v0
	v_sub_f32_e32 v0, v109, v138
	v_exp_f32_e32 v146, v2
	v_sub_f32_e32 v2, v91, v137
	v_exp_f32_e32 v109, v0
	v_sub_f32_e32 v0, v110, v138
	v_exp_f32_e32 v147, v2
	v_sub_f32_e32 v2, v92, v137
	v_exp_f32_e32 v110, v0
	v_sub_f32_e32 v0, v111, v138
	v_exp_f32_e32 v148, v2
	v_sub_f32_e32 v2, v93, v137
	v_exp_f32_e32 v111, v0
	v_sub_f32_e32 v0, v112, v138
	v_exp_f32_e32 v149, v2
	v_sub_f32_e32 v2, v94, v137
	v_exp_f32_e32 v112, v0
	v_sub_f32_e32 v0, v113, v138
	v_exp_f32_e32 v150, v2
	v_sub_f32_e32 v2, v95, v137
	v_exp_f32_e32 v113, v0
	v_sub_f32_e32 v0, v114, v138
	v_exp_f32_e32 v151, v2
	v_sub_f32_e32 v2, v96, v137
	v_exp_f32_e32 v114, v0
	v_sub_f32_e32 v0, v115, v138
	v_exp_f32_e32 v152, v2
	v_sub_f32_e32 v2, v97, v137
	v_exp_f32_e32 v115, v0
	v_sub_f32_e32 v0, v84, v137
	v_exp_f32_e32 v153, v2
	v_sub_f32_e32 v2, v98, v137
	v_exp_f32_e32 v0, v0
	v_exp_f32_e32 v154, v2
	v_sub_f32_e32 v2, v99, v137
	v_cvt_pk_bf16_f32 v162, v157, v158
	v_cvt_pk_bf16_f32 v163, v159, v160
	v_cvt_pk_bf16_f32 v164, v104, v105
	v_cvt_pk_bf16_f32 v165, v106, v107
	v_exp_f32_e32 v155, v2
	v_cvt_pk_bf16_f32 v84, v0, v141
	v_cvt_pk_bf16_f32 v85, v142, v143
	v_cvt_pk_bf16_f32 v86, v144, v145
	v_cvt_pk_bf16_f32 v87, v146, v147
	v_cvt_pk_bf16_f32 v100, v108, v109
	v_cvt_pk_bf16_f32 v101, v110, v111
	v_cvt_pk_bf16_f32 v102, v112, v113
	v_cvt_pk_bf16_f32 v103, v114, v115
	v_cvt_pk_bf16_f32 v88, v148, v149
	v_cvt_pk_bf16_f32 v89, v150, v151
	v_cvt_pk_bf16_f32 v90, v152, v153
	v_cvt_pk_bf16_f32 v91, v154, v155
	s_waitcnt lgkmcnt(0)
	s_barrier
	v_mfma_f32_16x16x32_bf16 v[80:83], v[216:219], v[162:165], v[80:83]
	v_mfma_f32_16x16x32_bf16 v[92:95], v[216:219], v[84:87], v[76:79]
	s_waitcnt vmcnt(2)
	ds_write_b128 v129, v[40:43]
	v_mfma_f32_16x16x32_bf16 v[76:79], v[220:223], v[100:103], v[80:83]
	v_mfma_f32_16x16x32_bf16 v[80:83], v[220:223], v[88:91], v[92:95]
	ds_write_b128 v129, v[36:39] offset:16
	v_mfma_f32_16x16x32_bf16 v[72:75], v[224:227], v[162:165], v[72:75]
	v_mfma_f32_16x16x32_bf16 v[92:95], v[224:227], v[84:87], v[68:71]
	s_waitcnt vmcnt(0)
	ds_write2_b64 v156, v[48:49], v[50:51] offset0:128 offset1:130
	v_mfma_f32_16x16x32_bf16 v[68:71], v[228:231], v[100:103], v[72:75]
	v_mfma_f32_16x16x32_bf16 v[72:75], v[228:231], v[88:91], v[92:95]
	ds_write2_b64 v156, v[44:45], v[46:47] offset0:132 offset1:134
	v_mfma_f32_16x16x32_bf16 v[64:67], v[232:235], v[162:165], v[64:67]
	v_mfma_f32_16x16x32_bf16 v[92:95], v[232:235], v[84:87], v[60:63]
	v_mfma_f32_16x16x32_bf16 v[60:63], v[240:243], v[100:103], v[64:67]
	v_mfma_f32_16x16x32_bf16 v[64:67], v[240:243], v[88:91], v[92:95]
	v_mfma_f32_16x16x32_bf16 v[56:59], v[244:247], v[162:165], v[56:59]
	v_mfma_f32_16x16x32_bf16 v[84:87], v[244:247], v[84:87], v[52:55]
	v_mfma_f32_16x16x32_bf16 v[52:55], v[248:251], v[100:103], v[56:59]
	v_mfma_f32_16x16x32_bf16 v[56:59], v[248:251], v[88:91], v[84:87]
	s_waitcnt lgkmcnt(0)
	s_barrier
	s_cmpk_gt_u32 s12, 0x44
	s_cbranch_scc1 .LBB0_357
	s_cmp_gt_u32 s12, 4
	s_mov_b64 s[8:9], -1
	s_cbranch_scc0 .LBB0_354
	v_add_u32_e32 v2, s10, v136
	v_add_u32_e32 v2, 0x2040, v2
	v_mad_i64_i32 v[2:3], s[8:9], v2, s33, v[124:125]
	s_add_i32 s72, s10, 64
	s_mov_b64 s[8:9], 0

.LBB0_357:
	ds_read_b128 v[166:169], v134
	ds_read_b128 v[170:173], v134 offset:64
	ds_read_b128 v[174:177], v134 offset:2304
	ds_read_b128 v[178:181], v134 offset:2368
	ds_read_b128 v[196:199], v134 offset:4608
	ds_read_b128 v[200:203], v134 offset:4672
	ds_read_b128 v[204:207], v134 offset:6912
	ds_read_b128 v[212:215], v134 offset:6976
	ds_read_b128 v[216:219], v135 offset:9216
	ds_read_b128 v[220:223], v135 offset:9280
	ds_read_b128 v[224:227], v135 offset:11520
	ds_read_b128 v[228:231], v135 offset:11584
	ds_read_b128 v[232:235], v135 offset:13824
	ds_read_b128 v[240:243], v135 offset:13888
	v_add_f32_e32 v2, 0, v157
	v_add_f32_e32 v2, v158, v2
	v_add_f32_e32 v2, v159, v2
	v_add_f32_e32 v2, v160, v2
	v_add_f32_e32 v2, v104, v2
	v_add_f32_e32 v2, v105, v2
	v_add_f32_e32 v2, v106, v2
	v_add_f32_e32 v2, v107, v2
	v_add_f32_e32 v2, v108, v2
	v_add_f32_e32 v2, v109, v2
	v_add_f32_e32 v2, v110, v2
	v_add_f32_e32 v2, v111, v2
	v_add_f32_e32 v2, v112, v2
	v_add_f32_e32 v2, v113, v2
	v_add_f32_e32 v2, v114, v2
	v_add_f32_e32 v2, v115, v2
	v_add_f32_e32 v2, v140, v2
	s_waitcnt lgkmcnt(13)
	v_mfma_f32_16x16x32_bf16 v[88:91], v[166:169], v[4:7], 0
	v_mfma_f32_16x16x32_bf16 v[84:87], v[166:169], v[12:15], 0
	ds_read_b128 v[244:247], v135 offset:16128
	ds_read_b128 v[248:251], v135 offset:16192
	s_waitcnt lgkmcnt(14)
	v_mfma_f32_16x16x32_bf16 v[88:91], v[170:173], v[8:11], v[88:91]
	v_mfma_f32_16x16x32_bf16 v[84:87], v[170:173], v[16:19], v[84:87]
	s_waitcnt lgkmcnt(13)
	v_mfma_f32_16x16x32_bf16 v[104:107], v[174:177], v[4:7], 0
	v_mfma_f32_16x16x32_bf16 v[92:95], v[174:177], v[12:15], 0
	s_waitcnt lgkmcnt(12)
	v_mfma_f32_16x16x32_bf16 v[104:107], v[178:181], v[8:11], v[104:107]
	v_mfma_f32_16x16x32_bf16 v[92:95], v[178:181], v[16:19], v[92:95]
	s_waitcnt lgkmcnt(11)
	v_mfma_f32_16x16x32_bf16 v[108:111], v[196:199], v[4:7], 0
	v_mfma_f32_16x16x32_bf16 v[96:99], v[196:199], v[12:15], 0
	v_max3_f32 v3, v88, s54, v89
	v_max3_f32 v3, v3, v90, v91
	s_waitcnt lgkmcnt(10)
	v_mfma_f32_16x16x32_bf16 v[108:111], v[200:203], v[8:11], v[108:111]
	v_mfma_f32_16x16x32_bf16 v[96:99], v[200:203], v[16:19], v[96:99]
	s_waitcnt lgkmcnt(9)
	v_mfma_f32_16x16x32_bf16 v[112:115], v[204:207], v[4:7], 0
	v_mfma_f32_16x16x32_bf16 v[100:103], v[204:207], v[12:15], 0
	v_max3_f32 v3, v3, v104, v105
	v_max3_f32 v3, v3, v106, v107
	s_waitcnt lgkmcnt(8)
	v_mfma_f32_16x16x32_bf16 v[112:115], v[212:215], v[8:11], v[112:115]
	v_mfma_f32_16x16x32_bf16 v[100:103], v[212:215], v[16:19], v[100:103]
	v_max3_f32 v3, v3, v108, v109
	v_max3_f32 v3, v3, v110, v111
	s_nop 5
	v_max3_f32 v3, v3, v112, v113
	v_max3_f32 v3, v3, v114, v115
	v_mov_b32_e32 v140, v3
	s_nop 1
	v_permlane16_swap_b32_e32 v3, v140
	v_max_f32_e32 v140, v140, v140
	v_max_f32_e32 v3, v3, v3
	v_max_f32_e32 v3, v3, v140
	v_mov_b32_e32 v140, v3
	s_nop 1
	v_permlane32_swap_b32_e32 v3, v140
	v_max_f32_e32 v140, v140, v140
	v_max_f32_e32 v3, v3, v3
	v_max_f32_e32 v3, v3, v140
	v_add_f32_e32 v140, 0x41000000, v138
	v_cmp_gt_f32_e32 vcc, v3, v140
	s_cbranch_vccz .LBB0_359
	v_max_f32_e32 v3, v3, v3
	v_max_f32_e32 v140, v138, v138
	v_max_f32_e32 v3, v140, v3
	v_sub_f32_e32 v138, v138, v3
	v_exp_f32_e32 v138, v138
	s_nop 0
	v_mul_f32_e32 v2, v2, v138
	v_pk_mul_f32 v[78:79], v[78:79], v[138:139] op_sel_hi:[1,0]
	v_pk_mul_f32 v[76:77], v[76:77], v[138:139] op_sel_hi:[1,0]
	v_pk_mul_f32 v[70:71], v[70:71], v[138:139] op_sel_hi:[1,0]
	v_pk_mul_f32 v[68:69], v[68:69], v[138:139] op_sel_hi:[1,0]
	v_pk_mul_f32 v[62:63], v[62:63], v[138:139] op_sel_hi:[1,0]
	v_pk_mul_f32 v[60:61], v[60:61], v[138:139] op_sel_hi:[1,0]
	v_pk_mul_f32 v[54:55], v[54:55], v[138:139] op_sel_hi:[1,0]
	v_pk_mul_f32 v[52:53], v[52:53], v[138:139] op_sel_hi:[1,0]
	v_mov_b32_e32 v138, v3

.LBB0_361:
	v_sub_f32_e32 v3, v88, v138
	v_exp_f32_e32 v3, v3
	v_sub_f32_e32 v89, v89, v138
	v_exp_f32_e32 v139, v89
	v_sub_f32_e32 v89, v90, v138
	v_exp_f32_e32 v141, v89
	v_sub_f32_e32 v89, v91, v138
	v_exp_f32_e32 v142, v89
	v_sub_f32_e32 v89, v104, v138
	v_add_f32_e32 v88, 0, v3
	v_exp_f32_e32 v143, v89
	v_sub_f32_e32 v89, v105, v138
	v_add_f32_e32 v88, v139, v88
	v_exp_f32_e32 v144, v89
	v_sub_f32_e32 v89, v106, v138
	v_add_f32_e32 v88, v141, v88
	v_exp_f32_e32 v145, v89
	v_sub_f32_e32 v89, v107, v138
	v_add_f32_e32 v88, v142, v88
	v_exp_f32_e32 v107, v89
	v_sub_f32_e32 v89, v108, v138
	v_add_f32_e32 v88, v143, v88
	v_exp_f32_e32 v89, v89
	v_sub_f32_e32 v90, v109, v138
	v_add_f32_e32 v88, v144, v88
	v_exp_f32_e32 v90, v90
	v_sub_f32_e32 v91, v110, v138
	v_add_f32_e32 v88, v145, v88
	v_exp_f32_e32 v91, v91
	v_sub_f32_e32 v104, v111, v138
	v_add_f32_e32 v88, v107, v88
	v_exp_f32_e32 v104, v104
	v_sub_f32_e32 v105, v112, v138
	v_add_f32_e32 v88, v89, v88
	v_exp_f32_e32 v105, v105
	v_sub_f32_e32 v106, v113, v138
	v_add_f32_e32 v88, v90, v88
	v_exp_f32_e32 v106, v106
	v_sub_f32_e32 v108, v114, v138
	v_add_f32_e32 v88, v91, v88
	v_exp_f32_e32 v108, v108
	v_sub_f32_e32 v109, v115, v138
	v_add_f32_e32 v88, v104, v88
	v_exp_f32_e32 v109, v109
	v_add_f32_e32 v88, v105, v88
	v_add_f32_e32 v88, v106, v88
	v_add_f32_e32 v88, v108, v88
	v_add_f32_e32 v88, v109, v88
	v_add_f32_e32 v140, v2, v88
	v_sub_f32_e32 v2, v84, v137
	v_exp_f32_e32 v2, v2
	v_sub_f32_e32 v84, v85, v137
	v_exp_f32_e32 v84, v84
	v_sub_f32_e32 v85, v86, v137
	v_exp_f32_e32 v85, v85
	v_sub_f32_e32 v86, v87, v137
	v_exp_f32_e32 v86, v86
	v_sub_f32_e32 v87, v92, v137
	v_cvt_pk_bf16_f32 v88, v89, v90
	v_cvt_pk_bf16_f32 v89, v91, v104
	v_cvt_pk_bf16_f32 v104, v3, v139
	v_add_f32_e32 v3, 0, v2
	v_exp_f32_e32 v87, v87
	v_sub_f32_e32 v92, v93, v137
	v_cvt_pk_bf16_f32 v91, v108, v109
	v_add_f32_e32 v3, v84, v3
	v_exp_f32_e32 v108, v92
	v_sub_f32_e32 v92, v94, v137
	v_add_f32_e32 v3, v85, v3
	v_exp_f32_e32 v109, v92
	v_sub_f32_e32 v92, v95, v137
	v_add_f32_e32 v3, v86, v3
	v_exp_f32_e32 v95, v92
	v_sub_f32_e32 v92, v96, v137
	v_add_f32_e32 v3, v87, v3
	v_exp_f32_e32 v96, v92
	v_sub_f32_e32 v92, v97, v137
	v_add_f32_e32 v3, v108, v3
	v_exp_f32_e32 v97, v92
	v_sub_f32_e32 v92, v98, v137
	v_add_f32_e32 v3, v109, v3
	v_exp_f32_e32 v98, v92
	v_sub_f32_e32 v92, v99, v137
	v_add_f32_e32 v3, v95, v3
	v_exp_f32_e32 v99, v92
	v_sub_f32_e32 v92, v100, v137
	v_add_f32_e32 v3, v96, v3
	v_exp_f32_e32 v100, v92
	v_sub_f32_e32 v92, v101, v137
	v_add_f32_e32 v3, v97, v3
	v_exp_f32_e32 v101, v92
	v_sub_f32_e32 v92, v102, v137
	v_add_f32_e32 v3, v98, v3
	v_exp_f32_e32 v102, v92
	v_sub_f32_e32 v92, v103, v137
	v_add_f32_e32 v3, v99, v3
	v_exp_f32_e32 v103, v92
	v_cvt_pk_bf16_f32 v92, v2, v84
	v_cvt_pk_bf16_f32 v93, v85, v86
	v_cvt_pk_bf16_f32 v84, v96, v97
	v_cvt_pk_bf16_f32 v85, v98, v99
	v_add_f32_e32 v3, v100, v3
	v_add_f32_e32 v3, v101, v3
	v_add_f32_e32 v3, v102, v3
	v_add_f32_e32 v3, v103, v3
	v_cvt_pk_bf16_f32 v94, v87, v108
	v_cvt_pk_bf16_f32 v86, v100, v101
	v_cvt_pk_bf16_f32 v87, v102, v103
	v_cvt_pk_bf16_f32 v90, v105, v106
	v_cvt_pk_bf16_f32 v105, v141, v142
	v_cvt_pk_bf16_f32 v106, v143, v144
	v_cvt_pk_bf16_f32 v107, v145, v107
	v_cvt_pk_bf16_f32 v95, v109, v95
	s_mov_b64 s[8:9], 0x4000
	v_add_f32_e32 v139, v0, v3
	s_addk_i32 s10, 0x80
	v_lshl_add_u64 v[126:127], v[126:127], 0, s[8:9]
	s_waitcnt lgkmcnt(0)
	s_barrier
	v_mfma_f32_16x16x32_bf16 v[76:79], v[216:219], v[104:107], v[76:79]
	v_mfma_f32_16x16x32_bf16 v[96:99], v[216:219], v[92:95], v[80:83]
	s_waitcnt vmcnt(6)
	ds_write_b128 v129, v[24:27]
	v_mfma_f32_16x16x32_bf16 v[80:83], v[220:223], v[88:91], v[76:79]
	v_mfma_f32_16x16x32_bf16 v[76:79], v[220:223], v[84:87], v[96:99]
	ds_write_b128 v129, v[20:23] offset:16
	v_mfma_f32_16x16x32_bf16 v[68:71], v[224:227], v[104:107], v[68:71]
	v_mfma_f32_16x16x32_bf16 v[96:99], v[224:227], v[92:95], v[72:75]
	s_waitcnt vmcnt(4)
	ds_write2_b64 v156, v[32:33], v[34:35] offset0:128 offset1:130
	v_mfma_f32_16x16x32_bf16 v[72:75], v[228:231], v[88:91], v[68:71]
	v_mfma_f32_16x16x32_bf16 v[68:71], v[228:231], v[84:87], v[96:99]
	ds_write2_b64 v156, v[28:29], v[30:31] offset0:132 offset1:134
	v_mfma_f32_16x16x32_bf16 v[60:63], v[232:235], v[104:107], v[60:63]
	v_mfma_f32_16x16x32_bf16 v[96:99], v[232:235], v[92:95], v[64:67]
	v_mfma_f32_16x16x32_bf16 v[64:67], v[240:243], v[88:91], v[60:63]
	v_mfma_f32_16x16x32_bf16 v[60:63], v[240:243], v[84:87], v[96:99]
	v_mfma_f32_16x16x32_bf16 v[52:55], v[244:247], v[104:107], v[52:55]
	v_mfma_f32_16x16x32_bf16 v[92:95], v[244:247], v[92:95], v[56:59]
	v_mfma_f32_16x16x32_bf16 v[56:59], v[248:251], v[88:91], v[52:55]
	v_mfma_f32_16x16x32_bf16 v[52:55], v[248:251], v[84:87], v[92:95]
	s_waitcnt lgkmcnt(0)
	s_barrier
	s_andn2_b64 vcc, exec, s[6:7]
	s_cbranch_vccz .LBB0_363
	s_mov_b32 s12, s11
	s_add_i32 s11, s12, 2
	s_cmpk_gt_u32 s12, 0x45
	s_cselect_b64 s[6:7], -1, 0
	s_and_b64 vcc, exec, s[6:7]
	s_branch .Lattn_d_top
